# attention units in XCD-local order (contiguous query rows per XCD for K/V L2 reuse)
# baseline (speedup 1.0000x reference)
; #define LAS __attribute__((address_space(3)))
; #define FRESH_KP KP Pp; { unsigned long long ki_ = (unsigned long long)__builtin_amdgcn_kernarg_segment_ptr(); asm volatile("" : "+s"(ki_)); Pp = (KP)ki_; }
; __device__ __forceinline__ void attn_mfma(LAS unsigned char* lds, int layer, int G, const int wave_s) {
;     FRESH_IDS; FRESH_KP;
;     unsigned char* ws = Pp->ws;
;     const bf16_t* Q = (const bf16_t*)(ws + WS_Q); const bf16_t* Kb = (const bf16_t*)(ws + WS_K); const bf16_t* Vb = (const bf16_t*)(ws + WS_V);
;     bf16_t* YM = (bf16_t*)(ws + WS_YM); const float* ZT = (const float*)(ws + WS_SSHY);
;     const float* gat = Pp->in[20] + layer * ATTW; const float* ghy = Pp->in[19] + layer * HY;
;     const int r32 = lane & 31, hi = lane >> 5, h = wave, kv = h >> 2;
;     const float sk = Pp->in[18][layer * NH + h] * LOG2E;
;     const unsigned lbase = (unsigned)(uintptr_t)lds;
;     LAS float* al_l = (LAS float*)(lds + AT_SCR) + wave * 64; LAS float* li_l = al_l + 32;
;     LAS float* xa = (LAS float*)(lds + AT_XA); LAS float* xh = (LAS float*)(lds + AT_XH);
;     const int nunits = layer == DEPTH - 1 ? ML / 32 : MT / 32;
;     for (int unit = blockIdx.x; unit < nunits; unit += G) {
.LBB0_785:
	s_andn2_b64 vcc, exec, s[36:37]
	s_cbranch_vccnz .LBB0_884
	s_cmp_lg_u32 s76, 3
	s_cselect_b64 s[44:45], -1, 0
	s_and_b64 s[0:1], s[44:45], exec
	s_movk_i32 s0, 0x110
	s_cselect_b32 s0, s0, 0x100
	s_cmp_ge_i32 s2, s0
	v_readlane_b32 s17, v253, 2
	s_mov_b64 s[36:37], s[94:95]
	v_mbcnt_lo_u32_b32 v0, -1, 0
	v_mbcnt_hi_u32_b32 v0, -1, v0
	s_cbranch_scc1 .LBB0_826
	s_load_dwordx2 s[40:41], s[36:37], 0xd8
	s_lshl_b32 s10, s76, 3
	s_lshl_b32 s1, s17, 6
	v_and_b32_e32 v184, 31, v0
	s_waitcnt vmcnt(0)
	v_lshlrev_b32_e32 v4, 4, v0
	s_waitcnt lgkmcnt(0)
	s_add_u32 s46, s40, 0xac20000
	s_addc_u32 s47, s41, 0
	s_add_u32 s48, s40, 0xb060000
	s_addc_u32 s49, s41, 0
	s_add_u32 s42, s40, 0xb4a0000
	s_addc_u32 s43, s41, 0
	s_add_i32 s10, s17, s10
	s_ashr_i32 s11, s10, 31
	s_lshl_b64 s[38:39], s[10:11], 2
	s_load_dwordx2 s[10:11], s[36:37], 0x90
	s_load_dwordx4 s[52:55], s[36:37], 0x98
	v_and_b32_e32 v6, 0xc0, v4
	v_lshlrev_b32_e32 v7, 1, v0
	v_and_b32_e32 v7, 32, v7
	s_waitcnt lgkmcnt(0)
	s_add_u32 s10, s10, s38
	s_addc_u32 s11, s11, s39
	global_load_dword v2, v1, s[10:11]
	s_lshl_b32 s10, s17, 8
	s_add_i32 s15, s10, 0
	s_lshl_b32 s26, s76, 10
	s_add_i32 s15, s15, 0x20000
	s_lshl_b64 s[10:11], s[26:27], 2
	s_add_u32 s56, s52, s10
	s_addc_u32 s57, s53, s11
	s_add_u32 s54, s54, s10
	s_addc_u32 s55, s55, s11
	s_lshl_b32 s60, s17, 7
	s_ashr_i32 s61, s60, 31
	s_lshl_b64 s[52:53], s[60:61], 1
	s_add_u32 s10, s40, s52
	s_addc_u32 s11, s41, s53
	s_add_u32 s50, s10, 0x9b20000
	s_addc_u32 s51, s11, 0
	s_lshl_b32 s10, s17, 12
	s_and_b32 s10, s10, 0xffffc000
	s_add_i32 s11, s10, 0
	v_lshl_add_u32 v188, v184, 8, s11
	s_add_i32 s11, 0, 0x8000
	v_add_u32_e32 v6, s11, v6
	v_ashrrev_i32_e32 v185, 5, v0
	v_mov_b32_e32 v163, v1
	s_mulk_i32 s17, 0x2200
	v_lshlrev_b32_e32 v187, 4, v185
	v_cmp_gt_u32_e64 s[36:37], 32, v0
	s_mov_b64 s[28:29], 0xd6a0000
	s_add_i32 s17, s17, 0
	v_ashrrev_i32_e32 v194, 4, v0
	v_lshl_add_u32 v193, v184, 1, s17
	v_lshlrev_b32_e32 v189, 2, v185
	v_lshlrev_b32_e32 v5, 2, v184
	v_readlane_b32 s23, v255, 7
	s_add_i32 s11, s60, 0
	s_add_i32 s11, s11, 0x20c00
	v_add_u32_e32 v190, s15, v5
	v_add_u32_e32 v209, s15, v187
	s_movk_i32 s15, 0x440
	v_cmp_eq_u32_e64 s[38:39], 0, v184
	s_waitcnt vmcnt(0)
	v_mul_f32_e32 v186, 0x3fb8aa3b, v2
	v_lshlrev_b32_e32 v2, 3, v0
	v_and_b32_e32 v3, 24, v2
	v_and_b32_e32 v2, 0x100, v2
	v_add3_u32 v3, v6, v3, v7
	v_add3_u32 v191, v3, v2, s10
	v_and_b32_e32 v2, 7, v0
	v_lshlrev_b32_e32 v162, 4, v2
	v_and_b32_e32 v6, -8, v0
	v_lshlrev_b32_e32 v192, 2, v2
	v_lshl_add_u64 v[2:3], s[40:41], 0, v[162:163]
	v_cmp_gt_i32_e64 s[40:41], 8, v0
	v_and_b32_e32 v0, 0xf0, v4
	v_lshl_add_u64 v[164:165], v[2:3], 0, s[28:29]
	v_add_u32_e32 v196, s17, v0
	s_movk_i32 s17, 0x70
	v_add_u32_e32 v3, 32, v187
	v_bitop3_b32 v202, v3, v4, s17 bitop3:0x78
	v_add_u32_e32 v3, 64, v187
	v_bitop3_b32 v203, v3, v4, s17 bitop3:0x78
	v_add_u32_e32 v3, 0x60, v187
	v_bitop3_b32 v204, v3, v4, s17 bitop3:0x78
	v_add_u32_e32 v3, 0x80, v187
	v_bitop3_b32 v205, v3, v4, s17 bitop3:0x78
	v_add_u32_e32 v3, 0xa0, v187
	v_bitop3_b32 v206, v3, v4, s17 bitop3:0x78
	v_add_u32_e32 v3, 0xc0, v187
	v_bitop3_b32 v207, v3, v4, s17 bitop3:0x78
	v_add_u32_e32 v3, 0xe0, v187
	v_or_b32_e32 v2, s60, v184
	v_bitop3_b32 v200, v187, v4, s17 bitop3:0x78
	v_bitop3_b32 v208, v3, v4, s17 bitop3:0x78
	v_add_u32_e32 v4, s1, v6
	s_mov_b32 s17, 0x8800
	v_add_u32_e32 v6, 0x200, v4
	v_ashrrev_i32_e32 v3, 31, v2
	s_add_i32 s10, s23, s60
	v_add_u32_e32 v163, s23, v5
	s_movk_i32 s23, 0x110
	v_mad_i64_i32 v[166:167], s[28:29], v4, s17, 0
	v_mad_i64_i32 v[168:169], s[28:29], v6, s17, 0
	v_lshl_add_u64 v[180:181], v[2:3], 2, s[54:55]
	v_or_b32_e32 v3, 1, v189
	v_mul_lo_u32 v198, v194, s23
	v_ashrrev_i32_e32 v5, 31, v4
	v_mul_lo_u32 v210, v3, s23
	s_add_u32 s28, s42, s52
	v_ashrrev_i32_e32 v7, 31, v6
	v_lshl_add_u64 v[174:175], v[4:5], 2, s[56:57]
	v_lshl_add_u64 v[176:177], v[4:5], 1, s[42:43]
	v_mul_lo_u32 v2, v185, s15
	v_add_u32_e32 v3, 0x990, v210
	v_add_u32_e32 v4, 0x440, v198
	s_addc_u32 s29, s43, s53
	v_lshl_add_u64 v[178:179], v[6:7], 1, s[42:43]
	v_lshl_add_u64 v[182:183], s[28:29], 0, v[0:1]
	v_add_u32_e32 v211, v193, v2
	v_add_u32_e32 v212, v193, v3
	v_add_u32_e32 v213, v196, v4
	s_mov_b32 s15, s2
	s_cmpk_lg_u32 s3, 0x100
	s_cbranch_scc1 .Lattn_noperm
	s_and_b32 s15, s2, 7
	s_lshl_b32 s15, s15, 5
	s_lshr_b32 s17, s2, 3
	s_or_b32 s15, s15, s17

; #define LAS __attribute__((address_space(3)))
; __device__ __forceinline__ unsigned f2bf(float f) { unsigned u = __builtin_bit_cast(unsigned, f); return (u + 0x7fffu + ((u >> 16) & 1u)) >> 16; }
; __device__ __forceinline__ int crow(int r, int hi) { return (r & 3) + 8 * (r >> 2) + 4 * hi; }
; __device__ __forceinline__ void attn_mfma(LAS unsigned char* lds, int layer, int G, const int wave_s) {
;     ...
;         if (hi == 0) al_l[r32] = ra; asm volatile("s_waitcnt lgkmcnt(0)" ::: "memory");
;         { LAS unsigned char* ost = lds + AT_OST + wave * (32 * 272);
;           float gc[4];
; #pragma unroll
;           for (int d = 0; d < 4; ++d) gc[d] = gat[h * HD + 32 * d + r32];
; #pragma unroll
;           for (int r = 0; r < 16; ++r) { const int q = crow(r, hi); const float rq = al_l[q];
; #pragma unroll
;               for (int d = 0; d < 4; ++d) *(LAS bf16_t*)(ost + q * 272 + (32 * d + r32) * 2) = (bf16_t)f2bf(o[d][r] * rq * gc[d]); }
.LBB0_788:
	s_or_b64 exec, exec, s[54:55]
	s_waitcnt lgkmcnt(0)
	global_load_dword v8, v[180:181], off
	global_load_dword v7, v[180:181], off offset:128
	global_load_dword v6, v[180:181], off offset:256
	global_load_dword v0, v[180:181], off offset:384
	ds_read_b128 v[2:5], v209
	s_cmp_lt_i32 s15, s3
	s_cselect_b32 s15, s2, s15
	s_add_i32 s15, s15, s3
	s_cmp_lt_i32 s15, s0
	s_waitcnt lgkmcnt(0)
	v_mul_f32_e32 v9, v140, v2
	s_waitcnt vmcnt(3)
	v_mul_f32_e32 v9, v8, v9
	v_bfe_u32 v10, v9, 16, 1
	v_add3_u32 v9, v9, v10, s66
	ds_write_b16_d16_hi v211, v9
	v_mul_f32_e32 v9, v130, v2
	s_waitcnt vmcnt(2)
	v_mul_f32_e32 v9, v7, v9
	v_bfe_u32 v10, v9, 16, 1
	v_add3_u32 v9, v9, v10, s66
	ds_write_b16_d16_hi v211, v9 offset:64
	v_mul_f32_e32 v9, v128, v2
	s_waitcnt vmcnt(1)
	v_mul_f32_e32 v9, v6, v9
	v_bfe_u32 v10, v9, 16, 1
	v_mul_f32_e32 v2, v126, v2
	v_add3_u32 v9, v9, v10, s66
	s_waitcnt vmcnt(0)
	v_mul_f32_e32 v2, v0, v2
	ds_write_b16_d16_hi v211, v9 offset:128
	v_bfe_u32 v9, v2, 16, 1
	v_add3_u32 v2, v2, v9, s66
	ds_write_b16_d16_hi v211, v2 offset:192
	v_mul_f32_e32 v2, v141, v3
	v_mul_f32_e32 v2, v8, v2
	v_bfe_u32 v9, v2, 16, 1
	v_add3_u32 v2, v2, v9, s66
	v_add_u32_e32 v9, v193, v210
	ds_write_b16_d16_hi v9, v2
	v_mul_f32_e32 v2, v131, v3
	v_mul_f32_e32 v2, v7, v2
	v_bfe_u32 v10, v2, 16, 1
	v_add3_u32 v2, v2, v10, s66
	ds_write_b16_d16_hi v9, v2 offset:64
	v_mul_f32_e32 v2, v129, v3
	v_mul_f32_e32 v2, v6, v2
	v_bfe_u32 v10, v2, 16, 1
	v_add3_u32 v2, v2, v10, s66
	ds_write_b16_d16_hi v9, v2 offset:128
	v_mul_f32_e32 v2, v127, v3
	v_mul_f32_e32 v2, v0, v2
	v_bfe_u32 v3, v2, 16, 1
	v_add3_u32 v2, v2, v3, s66
	ds_write_b16_d16_hi v9, v2 offset:192
	v_mul_f32_e32 v2, v138, v4
	v_mul_f32_e32 v2, v8, v2
	v_bfe_u32 v3, v2, 16, 1
	v_add3_u32 v2, v2, v3, s66
	ds_write_b16_d16_hi v9, v2 offset:272
	v_mul_f32_e32 v2, v134, v4
	v_mul_f32_e32 v2, v7, v2
	v_bfe_u32 v3, v2, 16, 1
	v_add3_u32 v2, v2, v3, s66
	ds_write_b16_d16_hi v9, v2 offset:336
	v_mul_f32_e32 v2, v136, v4
	v_mul_f32_e32 v2, v6, v2
	v_bfe_u32 v3, v2, 16, 1
	v_add3_u32 v2, v2, v3, s66
	ds_write_b16_d16_hi v9, v2 offset:400
	v_mul_f32_e32 v2, v132, v4
	v_mul_f32_e32 v2, v0, v2
	v_bfe_u32 v3, v2, 16, 1
	v_add3_u32 v2, v2, v3, s66
	ds_write_b16_d16_hi v9, v2 offset:464
	v_mul_f32_e32 v2, v139, v5
	v_mul_f32_e32 v2, v8, v2
	v_bfe_u32 v3, v2, 16, 1
	v_add3_u32 v2, v2, v3, s66
	ds_write_b16_d16_hi v9, v2 offset:544
	v_mul_f32_e32 v2, v135, v5
	v_mul_f32_e32 v2, v7, v2
	v_bfe_u32 v3, v2, 16, 1
	v_add3_u32 v2, v2, v3, s66
	ds_write_b16_d16_hi v9, v2 offset:608
	v_mul_f32_e32 v2, v137, v5
	v_mul_f32_e32 v2, v6, v2
	v_bfe_u32 v3, v2, 16, 1
	v_add3_u32 v2, v2, v3, s66
	ds_write_b16_d16_hi v9, v2 offset:672
	v_mul_f32_e32 v2, v133, v5
	v_mul_f32_e32 v2, v0, v2
	v_bfe_u32 v3, v2, 16, 1
	v_add3_u32 v2, v2, v3, s66
	ds_write_b16_d16_hi v9, v2 offset:736
	ds_read_b128 v[2:5], v209 offset:32
	s_waitcnt lgkmcnt(0)
	v_mul_f32_e32 v10, v100, v2
	v_mul_f32_e32 v10, v8, v10
	v_bfe_u32 v11, v10, 16, 1
	v_add3_u32 v10, v10, v11, s66
	ds_write_b16_d16_hi v9, v10 offset:1904
	v_mul_f32_e32 v10, v96, v2
	v_mul_f32_e32 v10, v7, v10
	v_bfe_u32 v11, v10, 16, 1
	v_add3_u32 v10, v10, v11, s66
	ds_write_b16_d16_hi v9, v10 offset:1968
	v_mul_f32_e32 v10, v98, v2
	v_mul_f32_e32 v10, v6, v10
	v_bfe_u32 v11, v10, 16, 1
	v_mul_f32_e32 v2, v94, v2
	v_add3_u32 v10, v10, v11, s66
	v_mul_f32_e32 v2, v0, v2
	ds_write_b16_d16_hi v9, v10 offset:2032
	v_bfe_u32 v10, v2, 16, 1
	v_add3_u32 v2, v2, v10, s66
	ds_write_b16_d16_hi v9, v2 offset:2096
	v_mul_f32_e32 v2, v101, v3
	v_mul_f32_e32 v2, v8, v2
	v_bfe_u32 v10, v2, 16, 1
	v_add3_u32 v2, v2, v10, s66
	ds_write_b16_d16_hi v9, v2 offset:2176
	v_mul_f32_e32 v2, v97, v3
	v_mul_f32_e32 v2, v7, v2
	v_bfe_u32 v10, v2, 16, 1
	v_add3_u32 v2, v2, v10, s66
	ds_write_b16_d16_hi v9, v2 offset:2240
	v_mul_f32_e32 v2, v99, v3
	v_mul_f32_e32 v2, v6, v2
	v_bfe_u32 v10, v2, 16, 1
	v_add3_u32 v2, v2, v10, s66
	ds_write_b16_d16_hi v9, v2 offset:2304
	v_mul_f32_e32 v2, v95, v3
	v_mul_f32_e32 v2, v0, v2
	v_bfe_u32 v3, v2, 16, 1
	v_add3_u32 v2, v2, v3, s66
	ds_write_b16_d16_hi v9, v2 offset:2368
	v_mul_f32_e32 v2, v108, v4
	v_mul_f32_e32 v2, v8, v2
	v_bfe_u32 v3, v2, 16, 1
	v_add3_u32 v2, v2, v3, s66
	ds_write_b16_d16_hi v9, v2 offset:2448
	v_mul_f32_e32 v2, v104, v4
	v_mul_f32_e32 v2, v7, v2
	v_bfe_u32 v3, v2, 16, 1
	v_add3_u32 v2, v2, v3, s66
	ds_write_b16_d16_hi v212, v2 offset:64
	v_mul_f32_e32 v2, v106, v4
	v_mul_f32_e32 v2, v6, v2
	v_bfe_u32 v3, v2, 16, 1
	v_add3_u32 v2, v2, v3, s66
	ds_write_b16_d16_hi v212, v2 offset:128
	v_mul_f32_e32 v2, v102, v4
	v_mul_f32_e32 v2, v0, v2
	v_bfe_u32 v3, v2, 16, 1
	v_add3_u32 v2, v2, v3, s66
	ds_write_b16_d16_hi v212, v2 offset:192
	v_mul_f32_e32 v2, v109, v5
	v_mul_f32_e32 v2, v8, v2
	v_bfe_u32 v3, v2, 16, 1
	v_add3_u32 v2, v2, v3, s66
	ds_write_b16_d16_hi v212, v2 offset:272
	v_mul_f32_e32 v2, v105, v5
	v_mul_f32_e32 v2, v7, v2
	v_bfe_u32 v3, v2, 16, 1
	v_add3_u32 v2, v2, v3, s66
	ds_write_b16_d16_hi v212, v2 offset:336
	v_mul_f32_e32 v2, v107, v5
	v_mul_f32_e32 v2, v6, v2
	v_bfe_u32 v3, v2, 16, 1
	v_add3_u32 v2, v2, v3, s66
	ds_write_b16_d16_hi v212, v2 offset:400
	v_mul_f32_e32 v2, v103, v5
	v_mul_f32_e32 v2, v0, v2
	v_bfe_u32 v3, v2, 16, 1
	v_add3_u32 v2, v2, v3, s66
	ds_write_b16_d16_hi v212, v2 offset:464
	ds_read_b128 v[2:5], v209 offset:64
	s_waitcnt lgkmcnt(0)
; #define LAS __attribute__((address_space(3)))
; __device__ __forceinline__ unsigned f2bf(float f) { unsigned u = __builtin_bit_cast(unsigned, f); return (u + 0x7fffu + ((u >> 16) & 1u)) >> 16; }
; __device__ __forceinline__ int crow(int r, int hi) { return (r & 3) + 8 * (r >> 2) + 4 * hi; }
; __device__ __forceinline__ void attn_mfma(LAS unsigned char* lds, int layer, int G, const int wave_s) {
;     ...
;           for (int r = 0; r < 16; ++r) { const int q = crow(r, hi); const float rq = al_l[q];
; #pragma unroll
;               for (int d = 0; d < 4; ++d) *(LAS bf16_t*)(ost + q * 272 + (32 * d + r32) * 2) = (bf16_t)f2bf(o[d][r] * rq * gc[d]); }
;           asm volatile("s_waitcnt lgkmcnt(0)" ::: "memory");
; #pragma unroll
;           for (int k = 0; k < 8; ++k) { const int q = k * 4 + (lane >> 4), ch = lane & 15;
;               const u32x4 v = *(const LAS u32x4*)(ost + q * 272 + ch * 16);
;               *(u32x4*)(YM + (size_t)(rowbase + q) * D + HY + h * HD + ch * 8) = v; } }
	v_mul_f32_e32 v9, v124, v2
	v_mul_f32_e32 v9, v8, v9
	v_bfe_u32 v10, v9, 16, 1
	v_add3_u32 v9, v9, v10, s66
	ds_write_b16_d16_hi v212, v9 offset:1632
	v_mul_f32_e32 v9, v122, v2
	v_mul_f32_e32 v9, v7, v9
	v_bfe_u32 v10, v9, 16, 1
	v_add3_u32 v9, v9, v10, s66
	ds_write_b16_d16_hi v212, v9 offset:1696
	v_mul_f32_e32 v9, v120, v2
	v_mul_f32_e32 v9, v6, v9
	v_bfe_u32 v10, v9, 16, 1
	v_mul_f32_e32 v2, v118, v2
	v_add3_u32 v9, v9, v10, s66
	v_mul_f32_e32 v2, v0, v2
	ds_write_b16_d16_hi v212, v9 offset:1760
	v_bfe_u32 v9, v2, 16, 1
	v_add3_u32 v2, v2, v9, s66
	ds_write_b16_d16_hi v212, v2 offset:1824
	v_mul_f32_e32 v2, v125, v3
	v_mul_f32_e32 v2, v8, v2
	v_bfe_u32 v9, v2, 16, 1
	v_add3_u32 v2, v2, v9, s66
	ds_write_b16_d16_hi v212, v2 offset:1904
	v_mul_f32_e32 v2, v123, v3
	v_mul_f32_e32 v2, v7, v2
	v_bfe_u32 v9, v2, 16, 1
	v_add3_u32 v2, v2, v9, s66
	ds_write_b16_d16_hi v212, v2 offset:1968
	v_mul_f32_e32 v2, v121, v3
	v_mul_f32_e32 v2, v6, v2
	v_bfe_u32 v9, v2, 16, 1
	v_add3_u32 v2, v2, v9, s66
	ds_write_b16_d16_hi v212, v2 offset:2032
	v_mul_f32_e32 v2, v119, v3
	v_mul_f32_e32 v2, v0, v2
	v_bfe_u32 v3, v2, 16, 1
	v_add3_u32 v2, v2, v3, s66
	ds_write_b16_d16_hi v212, v2 offset:2096
	v_mul_f32_e32 v2, v116, v4
	v_mul_f32_e32 v2, v8, v2
	v_bfe_u32 v3, v2, 16, 1
	v_add3_u32 v2, v2, v3, s66
	ds_write_b16_d16_hi v212, v2 offset:2176
	v_mul_f32_e32 v2, v114, v4
	v_mul_f32_e32 v2, v7, v2
	v_bfe_u32 v3, v2, 16, 1
	v_add3_u32 v2, v2, v3, s66
	ds_write_b16_d16_hi v212, v2 offset:2240
	v_mul_f32_e32 v2, v112, v4
	v_mul_f32_e32 v2, v6, v2
	v_bfe_u32 v3, v2, 16, 1
	v_add3_u32 v2, v2, v3, s66
	ds_write_b16_d16_hi v212, v2 offset:2304
	v_mul_f32_e32 v2, v110, v4
	v_mul_f32_e32 v2, v0, v2
	v_bfe_u32 v3, v2, 16, 1
	v_add3_u32 v2, v2, v3, s66
	ds_write_b16_d16_hi v212, v2 offset:2368
	v_mul_f32_e32 v2, v117, v5
	v_mul_f32_e32 v2, v8, v2
	v_bfe_u32 v3, v2, 16, 1
	v_add3_u32 v2, v2, v3, s66
	ds_write_b16_d16_hi v212, v2 offset:2448
	v_mul_f32_e32 v2, v115, v5
	v_mul_f32_e32 v2, v7, v2
	v_bfe_u32 v3, v2, 16, 1
	v_add3_u32 v2, v2, v3, s66
	ds_write_b16_d16_hi v212, v2 offset:2512
	v_mul_f32_e32 v2, v113, v5
	v_mul_f32_e32 v2, v6, v2
	v_bfe_u32 v3, v2, 16, 1
	v_add3_u32 v2, v2, v3, s66
	ds_write_b16_d16_hi v212, v2 offset:2576
	v_mul_f32_e32 v2, v111, v5
	v_mul_f32_e32 v2, v0, v2
	v_bfe_u32 v3, v2, 16, 1
	v_add3_u32 v2, v2, v3, s66
	ds_write_b16_d16_hi v212, v2 offset:2640
	ds_read_b128 v[2:5], v209 offset:96
	s_waitcnt lgkmcnt(0)
	v_mul_f32_e32 v9, v84, v2
	v_mul_f32_e32 v9, v8, v9
	v_bfe_u32 v10, v9, 16, 1
	v_add3_u32 v9, v9, v10, s66
	ds_write_b16_d16_hi v212, v9 offset:3808
	v_mul_f32_e32 v9, v80, v2
	v_mul_f32_e32 v9, v7, v9
	v_bfe_u32 v10, v9, 16, 1
	v_add3_u32 v9, v9, v10, s66
	ds_write_b16_d16_hi v212, v9 offset:3872
	v_mul_f32_e32 v9, v82, v2
	v_mul_f32_e32 v9, v6, v9
	v_bfe_u32 v10, v9, 16, 1
	v_mul_f32_e32 v2, v78, v2
	v_add3_u32 v9, v9, v10, s66
	v_mul_f32_e32 v2, v0, v2
	ds_write_b16_d16_hi v212, v9 offset:3936
	v_bfe_u32 v9, v2, 16, 1
	v_add3_u32 v2, v2, v9, s66
	ds_write_b16_d16_hi v212, v2 offset:4000
	v_mul_f32_e32 v2, v85, v3
	v_mul_f32_e32 v2, v8, v2
	v_bfe_u32 v9, v2, 16, 1
	v_add3_u32 v2, v2, v9, s66
	ds_write_b16_d16_hi v212, v2 offset:4080
	v_mul_f32_e32 v2, v81, v3
	v_mul_f32_e32 v2, v7, v2
	v_bfe_u32 v9, v2, 16, 1
	v_add3_u32 v2, v2, v9, s66
	ds_write_b16_d16_hi v212, v2 offset:4144
	v_mul_f32_e32 v2, v83, v3
	v_mul_f32_e32 v2, v6, v2
	v_bfe_u32 v9, v2, 16, 1
	v_add3_u32 v2, v2, v9, s66
	ds_write_b16_d16_hi v212, v2 offset:4208
	v_mul_f32_e32 v2, v79, v3
	v_mul_f32_e32 v2, v0, v2
	v_bfe_u32 v3, v2, 16, 1
	v_add3_u32 v2, v2, v3, s66
	ds_write_b16_d16_hi v212, v2 offset:4272
	v_mul_f32_e32 v2, v92, v4
	v_mul_f32_e32 v2, v8, v2
	v_bfe_u32 v3, v2, 16, 1
	v_add3_u32 v2, v2, v3, s66
	ds_write_b16_d16_hi v212, v2 offset:4352
	v_mul_f32_e32 v2, v88, v4
	v_mul_f32_e32 v2, v7, v2
	v_bfe_u32 v3, v2, 16, 1
	v_add3_u32 v2, v2, v3, s66
	ds_write_b16_d16_hi v212, v2 offset:4416
	v_mul_f32_e32 v2, v90, v4
	v_mul_f32_e32 v2, v6, v2
	v_bfe_u32 v3, v2, 16, 1
	v_add3_u32 v2, v2, v3, s66
	ds_write_b16_d16_hi v212, v2 offset:4480
	v_mul_f32_e32 v2, v86, v4
	v_mul_f32_e32 v2, v0, v2
	v_bfe_u32 v3, v2, 16, 1
	v_add3_u32 v2, v2, v3, s66
	ds_write_b16_d16_hi v212, v2 offset:4544
	v_mul_f32_e32 v2, v93, v5
	v_mul_f32_e32 v2, v8, v2
	v_bfe_u32 v3, v2, 16, 1
	v_add3_u32 v2, v2, v3, s66
	ds_write_b16_d16_hi v212, v2 offset:4624
	v_mul_f32_e32 v2, v89, v5
	v_mul_f32_e32 v2, v7, v2
	v_bfe_u32 v3, v2, 16, 1
	v_add3_u32 v2, v2, v3, s66
	ds_write_b16_d16_hi v212, v2 offset:4688
	v_mul_f32_e32 v2, v91, v5
	v_mul_f32_e32 v2, v6, v2
	v_bfe_u32 v3, v2, 16, 1
	v_add3_u32 v2, v2, v3, s66
	ds_write_b16_d16_hi v212, v2 offset:4752
	v_mul_f32_e32 v2, v87, v5
	v_mul_f32_e32 v0, v0, v2
	v_bfe_u32 v2, v0, 16, 1
	v_add3_u32 v0, v0, v2, s66
	ds_write_b16_d16_hi v212, v0 offset:4816
	s_waitcnt lgkmcnt(0)
	v_add_u32_e32 v0, v196, v198
	ds_read_b128 v[2:5], v0
	v_add_u32_e32 v6, s52, v194
	v_ashrrev_i32_e32 v7, 31, v6
	v_lshlrev_b64 v[8:9], 12, v[6:7]
	v_lshl_add_u64 v[8:9], v[182:183], 0, v[8:9]
	s_waitcnt lgkmcnt(0)
	global_store_dwordx4 v[8:9], v[2:5], off offset:2048
	ds_read_b128 v[2:5], v213
	v_add_u32_e32 v0, 4, v194
	v_add_u32_e32 v8, s52, v0
	v_ashrrev_i32_e32 v9, 31, v8
	v_lshlrev_b64 v[8:9], 12, v[8:9]
	v_lshl_add_u64 v[8:9], v[182:183], 0, v[8:9]
	s_waitcnt lgkmcnt(0)
	global_store_dwordx4 v[8:9], v[2:5], off offset:2048
	ds_read_b128 v[2:5], v213 offset:1088
	v_add_u32_e32 v8, 8, v6
	v_ashrrev_i32_e32 v9, 31, v8
	v_lshlrev_b64 v[8:9], 12, v[8:9]
	v_lshl_add_u64 v[8:9], v[182:183], 0, v[8:9]
	s_waitcnt lgkmcnt(0)
	global_store_dwordx4 v[8:9], v[2:5], off offset:2048
	ds_read_b128 v[2:5], v213 offset:2176
	v_add_u32_e32 v8, 12, v6
	v_ashrrev_i32_e32 v9, 31, v8
	v_lshlrev_b64 v[8:9], 12, v[8:9]
	v_lshl_add_u64 v[8:9], v[182:183], 0, v[8:9]
	s_waitcnt lgkmcnt(0)
	global_store_dwordx4 v[8:9], v[2:5], off offset:2048
	ds_read_b128 v[2:5], v213 offset:3264
	v_add_u32_e32 v8, 16, v6
	v_ashrrev_i32_e32 v9, 31, v8
	v_lshlrev_b64 v[8:9], 12, v[8:9]
	v_lshl_add_u64 v[8:9], v[182:183], 0, v[8:9]
	s_waitcnt lgkmcnt(0)
	global_store_dwordx4 v[8:9], v[2:5], off offset:2048
	ds_read_b128 v[2:5], v213 offset:4352
	v_add_u32_e32 v8, 20, v6
	v_ashrrev_i32_e32 v9, 31, v8
	v_lshlrev_b64 v[8:9], 12, v[8:9]
	v_lshl_add_u64 v[8:9], v[182:183], 0, v[8:9]
	s_waitcnt lgkmcnt(0)
	global_store_dwordx4 v[8:9], v[2:5], off offset:2048
	ds_read_b128 v[2:5], v213 offset:5440
	v_add_u32_e32 v8, 24, v6
	v_ashrrev_i32_e32 v9, 31, v8
	v_lshlrev_b64 v[8:9], 12, v[8:9]
	v_lshl_add_u64 v[8:9], v[182:183], 0, v[8:9]
	s_waitcnt lgkmcnt(0)
	global_store_dwordx4 v[8:9], v[2:5], off offset:2048
	ds_read_b128 v[2:5], v213 offset:6528
	v_add_u32_e32 v6, 28, v6
	v_ashrrev_i32_e32 v7, 31, v6
	v_lshlrev_b64 v[6:7], 12, v[6:7]
	v_lshl_add_u64 v[6:7], v[182:183], 0, v[6:7]
	s_waitcnt lgkmcnt(0)
	global_store_dwordx4 v[6:7], v[2:5], off offset:2048
	s_cbranch_scc0 .LBB0_826
